# v52 plus FFN1 tile-index computation with the group size hard-coded to 8 (shift/mask instead of a float-reciprocal division per tile)
# speedup vs baseline: 1.0078x; 1.0055x over previous
;     __host__ __device__ bool next(int i, Unit& u) const {
;         const long L = (long)i * G + c; if (L >= nwg) return false;
;         int wgid = (int)L; { const int q = nwg / NXCD, r = nwg % NXCD, xcd = wgid % NXCD, off = wgid / NXCD; wgid = (xcd < r ? xcd * (q + 1) : r * (q + 1) + (xcd - r) * q) + off; }
;         const int nig = wgm * nN, gid = wgid / nig, fm = gid * wgm, gsz = (nM - fm) < wgm ? (nM - fm) : wgm;
;         u.pm = fm + ((wgid % nig) % gsz); u.pn = (wgid % nig) / gsz; return true;
.LBB0_395:
	s_add_i32 s89, s89, 1
	s_mul_i32 s6, s89, s67
	s_mul_hi_u32 s7, s89, s26
	s_add_i32 s7, s7, s6
	s_mul_i32 s6, s89, s26
	s_add_u32 s6, s6, s2
	s_addc_u32 s7, s7, s33
	v_mov_b64_e32 v[2:3], 0xb00
	v_cmp_lt_i64_e64 s[8:9], s[6:7], v[2:3]
	v_mov_b64_e32 v[2:3], 0xaff
	v_cmp_gt_i64_e32 vcc, s[6:7], v[2:3]
	s_cbranch_vccnz .LBB0_397
	s_ashr_i32 s7, s6, 31
	s_lshr_b32 s7, s7, 29
	s_add_i32 s7, s6, s7
	s_ashr_i32 s16, s7, 3
	s_and_b32 s7, s7, -8
	s_sub_i32 s6, s6, s7
	s_cmp_lt_i32 s6, 0
	s_cselect_b32 s7, s51, 0x160
	s_mul_i32 s6, s7, s6
	s_add_i32 s6, s6, s16
	s_mul_hi_i32 s7, s6, 0x2e8ba2e9
	s_lshr_b32 s16, s7, 31
	s_ashr_i32 s7, s7, 6
	s_add_i32 s7, s7, s16
	s_lshl_b32 s16, s7, 3
	s_mulk_i32 s7, 0x160
	s_sub_i32 s6, s6, s7
	s_lshr_b32 s90, s6, 3
	s_and_b32 s6, s6, 7
	s_add_i32 s91, s6, s16
